# S4 and S7 GEMM K-loops: first iteration peeled (SrcC=0), accumulator-zeroing movs removed
# baseline (speedup 1.0000x reference)
; #define PG8_STAGE(bufoff, gbase, voff) do { _Pragma("unroll") for (int _i = 0; _i < 2; ++_i) \
;         __builtin_amdgcn_global_load_lds((const unsigned*)((const char*)(gbase) + (voff)[_i]), (PG8_LAS unsigned*)(lds + (bufoff) + ldsw + _i * 8192), 16, 0, 0); } while (0)
; #define PG8_WAIT_V(n) asm volatile("s_waitcnt vmcnt(" #n ")" ::: "memory")
; #define PG8_BAR __builtin_amdgcn_s_barrier()
; template <class Epi, class Sched, bool ALIGN_EPI = false, bool SP2 = false>
; __device__ __forceinline__ void gemm_phase(PG8_LAS unsigned char* lds, const Gemm g, const Sched& S, const Epi& E) {
;     ...
;     for (int i = 0; i < 2; ++i) { int R, C; stage_rc(tid * 16 + i * 8192, R, C); const int Rb = Epi::PERM ? ((R & ~31) + perm32(R & 31)) : R;
;         voffA[i] = (unsigned)(R * K + C) * 2u; voffB[i] = (unsigned)(Rb * K + C) * 2u; }
;     const size_t kstep = (size_t)(BK * 2);
;     const size_t hstep = (size_t)HALF * K * 2;
;     const size_t tstep = 2 * hstep;
;     const unsigned ldsw = (unsigned)wid * 1024u;
;     const int aoff = lds_byte(wr * 64 + fr, fq * 8), boff = lds_byte(wc * 32 + fr, fq * 8);
;     ...
;     f32x4 acc[2][2][4][2];
; #pragma unroll
;     for (int a = 0; a < 2; ++a)
; #pragma unroll
;         for (int b = 0; b < 2; ++b)
; #pragma unroll
;             for (int m = 0; m < 4; ++m)
; #pragma unroll
;                 for (int n = 0; n < 2; ++n) acc[a][b][m][n] = (f32x4){0.f, 0.f, 0.f, 0.f};
;     bf16x8 At[4][2], B0[2][2], B1[2][2];
;     const char* cA = (const char*)g.A + (size_t)cur.pm * tstep; const char* cB = (const char*)g.Bt + (size_t)cur.pn * tstep;
;     S.a_ready(cur);
;     if constexpr (SP2) {
;         PG8_STAGE(PG8_SB(0, 0), cB, voffB); PG8_STAGE(PG8_SB(0, 1), cB + hstep, voffB); PG8_STAGE(PG8_SA(0, 0), cA, voffA); PG8_STAGE(PG8_SA(0, 1), cA + hstep, voffA);
;         if (wr == 1) PG8_BAR;
;         PG8_WAIT_V(2); PG8_BAR;
;         PG8_STAGE(PG8_SB(1, 0), cB + kstep, voffB); PG8_STAGE(PG8_SA(1, 0), cA + kstep, voffA); PG8_STAGE(PG8_SB(1, 1), cB + hstep + kstep, voffB);
;         PG8_WAIT_V(6); PG8_BAR;
.LBB0_816:
	v_and_b32_e32 v178, 15, v154
	v_lshl_add_u64 v[8:9], s[14:15], 0, v[0:1]
	v_mov_b32_e32 v131, v1
	v_readlane_b32 s4, v253, 55
	v_lshlrev_b32_e32 v155, 6, v178
	v_lshlrev_b32_e32 v17, 2, v154
	v_lshl_add_u64 v[10:11], s[14:15], 0, v[130:131]
	v_mov_b32_e32 v135, v1
	v_readlane_b32 s5, v253, 56
	s_and_b32 s26, s22, 3
	s_lshl_b32 s0, s23, 13
	v_and_or_b32 v16, v154, 48, v155
	v_and_b32_e32 v17, 32, v17
	s_add_i32 m0, s30, 0x18000
	v_lshl_add_u64 v[8:9], v[8:9], 0, s[44:45]
	v_lshl_add_u64 v[12:13], s[4:5], 0, v[134:135]
	v_mov_b32_e32 v133, v1
	s_lshl_b32 s20, s23, 6
	v_bitop3_b32 v18, v16, s0, v17 bitop3:0xde
	s_lshl_b32 s0, s26, 12
	s_waitcnt vmcnt(2)
	s_barrier
	global_load_lds_dwordx4 v[8:9], off
	v_lshl_add_u64 v[8:9], v[10:11], 0, s[44:45]
	s_add_i32 m0, s30, 0x1a000
	s_add_i32 s35, s30, 0x8000
	s_add_i32 s36, s30, 0xa000
	v_lshl_add_u64 v[14:15], s[4:5], 0, v[132:133]
	v_bitop3_b32 v144, v16, s0, v17 bitop3:0xde
	global_load_lds_dwordx4 v[8:9], off
	v_lshl_add_u64 v[8:9], v[12:13], 0, s[44:45]
	s_mov_b32 m0, s35
	s_add_u32 s0, s14, 0x80080
	global_load_lds_dwordx4 v[8:9], off
	v_lshl_add_u64 v[8:9], v[14:15], 0, s[44:45]
	s_mov_b32 m0, s36
	s_addc_u32 s1, s15, 0
	global_load_lds_dwordx4 v[8:9], off
	s_add_i32 m0, s30, 0x1c000
	v_lshl_add_u64 v[8:9], s[0:1], 0, v[0:1]
	global_load_lds_dwordx4 v[8:9], off
	v_lshl_add_u64 v[8:9], s[0:1], 0, v[130:131]
	s_add_i32 m0, s30, 0x1e000
	v_readlane_b32 s0, v254, 4
	global_load_lds_dwordx4 v[8:9], off
	v_lshlrev_b32_e32 v8, 15, v6
	v_and_b32_e32 v8, 0xffff0000, v8
	v_lshl_add_u32 v5, v5, 12, v8
	v_and_b32_e32 v6, 1, v6
	v_lshl_or_b32 v5, v6, 6, v5
	v_lshl_add_u32 v136, v7, 1, v5
	v_lshlrev_b32_e32 v5, 15, v2
	v_and_b32_e32 v5, 0xffff0000, v5
	v_lshl_add_u32 v3, v3, 12, v5
	v_and_b32_e32 v2, 1, v2
	s_waitcnt vmcnt(6)
	v_lshl_or_b32 v2, v2, 6, v3
	v_lshl_add_u32 v138, v4, 1, v2
	v_mov_b32_e32 v137, v1
	v_mov_b32_e32 v139, v1
	s_mov_b32 s37, 0
	v_add_u32_e32 v145, 0, v18
	v_readlane_b32 s25, v253, 49
	s_mov_b32 s24, s0
	s_barrier
	v_readlane_b32 s1, v254, 5
	s_branch .LBB0_819

;     __device__ bool next(int i, Unit& u) const { const int j = first + i * G; if (j >= count) return false; u.pm = j / nN; u.pn = j % nN; return true; }
; #define PG8_STAGE(bufoff, gbase, voff) do { _Pragma("unroll") for (int _i = 0; _i < 2; ++_i) \
;         __builtin_amdgcn_global_load_lds((const unsigned*)((const char*)(gbase) + (voff)[_i]), (PG8_LAS unsigned*)(lds + (bufoff) + ldsw + _i * 8192), 16, 0, 0); } while (0)
; #define PG8_LDA(dst, b, h) do { _Pragma("unroll") for (int m = 0; m < 4; ++m) _Pragma("unroll") for (int k = 0; k < 2; ++k) dst[m][k] = *(const PG8_LAS bf16x8*)(lds + PG8_SA(b, h) + aoff + m * 2048 + k * 1024); } while (0)
; #define PG8_LDB(dst, b, h) do { _Pragma("unroll") for (int n = 0; n < 2; ++n) _Pragma("unroll") for (int k = 0; k < 2; ++k) dst[n][k] = *(const PG8_LAS bf16x8*)(lds + PG8_SB(b, h) + boff + n * 2048 + k * 1024); } while (0)
; #define PG8_WAIT_V(n) asm volatile("s_waitcnt vmcnt(" #n ")" ::: "memory")
; #define PG8_BAR __builtin_amdgcn_s_barrier()
; template <class Epi, class Sched, bool ALIGN_EPI = false, bool SP2 = false>
; __device__ __forceinline__ void gemm_phase(PG8_LAS unsigned char* lds, const Gemm g, const Sched& S, const Epi& E) {
;     ...
;         const bool has_next = S.next(ui + 1, nxt);
;         const char* nA = has_next ? (const char*)g.A + (size_t)nxt.pm * tstep : cA; const char* nB = has_next ? (const char*)g.Bt + (size_t)nxt.pn * tstep : cB;
;         for (int t = 0; t < nt; t += 2) {
;             const bool last = (t == nt - 2);
;             const char* a1 = cA + (size_t)(t + 1) * kstep;
;             const char* a2 = last ? nA : cA + (size_t)(t + 2) * kstep; const char* b2 = last ? nB : cB + (size_t)(t + 2) * kstep;
;             const char* a3 = a2 + kstep; const char* b3 = b2 + kstep;
;             if (last && has_next) S.a_ready(nxt);
;             if constexpr (SP2) {
;             PG8_LDB(B0, 0, 0); PG8_LDB(B1, 0, 1); PG8_SCHED; PG8_LDA(At, 0, 0); PG8_STAGE(PG8_SA(1, 1), a1 + hstep, voffA);
;             PG8_WAIT_V(8); PG8_WAIT_L(0); PG8_BAR; PG8_MMA(0, 0, At, B0); PG8_MMA(0, 1, At, B1); PG8_BAR; PG8_SCHED;
;             PG8_LDA(At, 0, 1); PG8_STAGE(PG8_SB(0, 0), b2, voffB); PG8_STAGE(PG8_SB(0, 1), b2 + hstep, voffB); PG8_STAGE(PG8_SA(0, 0), a2, voffA);
;             PG8_WAIT_V(8); PG8_WAIT_L(0); PG8_BAR; PG8_MMA(1, 0, At, B0); PG8_MMA(1, 1, At, B1); PG8_BAR; PG8_SCHED;
.LBB0_825:
	s_add_u32 s41, s14, 0x100
	s_addc_u32 s42, s15, 0
	s_ashr_i32 s9, s8, 31
	s_lshl_b64 s[10:11], s[8:9], 20
	v_readlane_b32 s7, v253, 53
	s_add_u32 s12, s7, s10
	v_readlane_b32 s7, v253, 54
	s_addc_u32 s13, s7, s11
	s_and_b64 s[10:11], s[2:3], exec
	s_cselect_b32 s9, s13, s5
	s_cselect_b32 s43, s12, s4
	s_ashr_i32 s7, s6, 31
	s_lshl_b64 s[10:11], s[6:7], 20
	s_add_u32 s10, s27, s10
	s_addc_u32 s11, s28, s11
	s_and_b64 s[16:17], s[2:3], exec
	s_cselect_b32 s7, s11, s15
	s_cselect_b32 s46, s10, s14
	s_add_u32 s14, s4, 0x80080
	s_addc_u32 s15, s5, 0
	v_lshl_add_u64 v[140:141], s[14:15], 0, v[136:137]
	v_lshl_add_u64 v[142:143], s[14:15], 0, v[138:139]
	s_mov_b32 s47, -2
	s_mov_b64 s[14:15], 0
	s_add_u32 s16, s4, s14
	s_addc_u32 s17, s5, s15
	s_add_u32 s16, s16, 0x100
	s_addc_u32 s17, s17, 0
	s_add_u32 s48, s41, s14
	s_addc_u32 s49, s42, s15
	s_add_i32 s50, 0, 0x10000
	s_cmpk_eq_i32 s14, 0xf00
	s_cselect_b32 s19, s9, s17
	s_cselect_b32 s18, s43, s16
	v_add_u32_e32 v160, s50, v144
	s_cselect_b32 s17, s7, s49
	s_cselect_b32 s16, s46, s48
	s_add_i32 s51, 0, 0x14000
	ds_read_b128 v[146:149], v160
	ds_read_b128 v[150:153], v160 offset:1024
	ds_read_b128 v[156:159], v160 offset:2048
	ds_read_b128 v[180:183], v160 offset:3072
	v_add_u32_e32 v160, s51, v144
	ds_read_b128 v[200:203], v160
	ds_read_b128 v[204:207], v160 offset:1024
	ds_read_b128 v[208:211], v160 offset:2048
	ds_read_b128 v[212:215], v160 offset:3072
	v_lshl_add_u64 v[160:161], v[140:141], 0, s[14:15]
	s_add_i32 m0, s30, 0xc000
	ds_read_b128 v[216:219], v145
	ds_read_b128 v[220:223], v145 offset:1024
	ds_read_b128 v[224:227], v145 offset:2048
	ds_read_b128 v[228:231], v145 offset:3072
	ds_read_b128 v[232:235], v145 offset:4096
	ds_read_b128 v[236:239], v145 offset:5120
	ds_read_b128 v[240:243], v145 offset:6144
	ds_read_b128 v[244:247], v145 offset:7168
	global_load_lds_dwordx4 v[160:161], off
	v_lshl_add_u64 v[160:161], v[142:143], 0, s[14:15]
	s_add_i32 m0, s30, 0xe000
	s_nop 0
	global_load_lds_dwordx4 v[160:161], off
	s_waitcnt vmcnt(8)
	s_waitcnt lgkmcnt(0)
	s_barrier
	s_setprio 1
	s_waitcnt lgkmcnt(0)
	v_mfma_f32_16x16x32_bf16 v[126:129], v[146:149], v[216:219], 0
	v_mfma_f32_16x16x32_bf16 v[122:125], v[156:159], v[216:219], 0
	v_mfma_f32_16x16x32_bf16 v[110:113], v[146:149], v[224:227], 0
	v_mfma_f32_16x16x32_bf16 v[106:109], v[156:159], v[224:227], 0
	v_mfma_f32_16x16x32_bf16 v[94:97], v[146:149], v[232:235], 0
	v_mfma_f32_16x16x32_bf16 v[90:93], v[156:159], v[232:235], 0
	v_mfma_f32_16x16x32_bf16 v[78:81], v[146:149], v[240:243], 0
	v_mfma_f32_16x16x32_bf16 v[74:77], v[156:159], v[240:243], 0
	v_mfma_f32_16x16x32_bf16 v[126:129], v[150:153], v[220:223], v[126:129]
	v_mfma_f32_16x16x32_bf16 v[122:125], v[180:183], v[220:223], v[122:125]
	v_mfma_f32_16x16x32_bf16 v[110:113], v[150:153], v[228:231], v[110:113]
	v_mfma_f32_16x16x32_bf16 v[106:109], v[180:183], v[228:231], v[106:109]
	v_mfma_f32_16x16x32_bf16 v[94:97], v[150:153], v[236:239], v[94:97]
	v_mfma_f32_16x16x32_bf16 v[90:93], v[180:183], v[236:239], v[90:93]
	v_mfma_f32_16x16x32_bf16 v[78:81], v[150:153], v[244:247], v[78:81]
	v_mfma_f32_16x16x32_bf16 v[74:77], v[180:183], v[244:247], v[74:77]
	s_setprio 0
	s_setprio 1
	v_mfma_f32_16x16x32_bf16 v[118:121], v[200:203], v[216:219], 0
	v_mfma_f32_16x16x32_bf16 v[114:117], v[208:211], v[216:219], 0
	v_mfma_f32_16x16x32_bf16 v[102:105], v[200:203], v[224:227], 0
	v_mfma_f32_16x16x32_bf16 v[98:101], v[208:211], v[224:227], 0
	v_mfma_f32_16x16x32_bf16 v[86:89], v[200:203], v[232:235], 0
	v_mfma_f32_16x16x32_bf16 v[82:85], v[208:211], v[232:235], 0
	v_mfma_f32_16x16x32_bf16 v[70:73], v[200:203], v[240:243], 0
	v_mfma_f32_16x16x32_bf16 v[66:69], v[208:211], v[240:243], 0
	v_mfma_f32_16x16x32_bf16 v[118:121], v[204:207], v[220:223], v[118:121]
	v_mfma_f32_16x16x32_bf16 v[114:117], v[212:215], v[220:223], v[114:117]
	v_mfma_f32_16x16x32_bf16 v[102:105], v[204:207], v[228:231], v[102:105]
	v_mfma_f32_16x16x32_bf16 v[98:101], v[212:215], v[228:231], v[98:101]
	v_mfma_f32_16x16x32_bf16 v[86:89], v[204:207], v[236:239], v[86:89]
	v_mfma_f32_16x16x32_bf16 v[82:85], v[212:215], v[236:239], v[82:85]
	v_mfma_f32_16x16x32_bf16 v[70:73], v[204:207], v[244:247], v[70:73]
	v_mfma_f32_16x16x32_bf16 v[66:69], v[212:215], v[244:247], v[66:69]
	s_setprio 0
	s_barrier
	s_add_i32 s48, s50, s29
	s_add_u32 s84, s16, s44
	s_addc_u32 s85, s17, s45
	s_mov_b32 m0, s48
	ds_read_b128 v[216:219], v145 offset:16384
	ds_read_b128 v[220:223], v145 offset:17408
	ds_read_b128 v[224:227], v145 offset:18432
	ds_read_b128 v[228:231], v145 offset:19456
	ds_read_b128 v[232:235], v145 offset:20480
	ds_read_b128 v[236:239], v145 offset:21504
	ds_read_b128 v[240:243], v145 offset:22528
	ds_read_b128 v[244:247], v145 offset:23552
	global_load_lds_dwordx4 v0, s[16:17]
	s_add_i32 m0, s48, 0x2000
	s_add_u32 s48, s16, 0x80000
	s_addc_u32 s49, s17, 0
	s_add_i32 s50, s51, s29
	global_load_lds_dwordx4 v130, s[16:17]
	s_mov_b32 m0, s50
	s_nop 0
	global_load_lds_dwordx4 v0, s[48:49]
	s_add_i32 m0, s50, 0x2000
	s_nop 0
	global_load_lds_dwordx4 v130, s[48:49]
	s_add_u32 s86, s18, s44
	s_addc_u32 s87, s19, s45
	s_mov_b32 m0, s30
	s_nop 0
	global_load_lds_dwordx4 v134, s[18:19]
	s_mov_b32 m0, s31
	s_nop 0
	global_load_lds_dwordx4 v132, s[18:19]
	s_waitcnt vmcnt(8)
	s_waitcnt lgkmcnt(0)
	s_barrier
; #define PG8_STAGE(bufoff, gbase, voff) do { _Pragma("unroll") for (int _i = 0; _i < 2; ++_i) \
;         __builtin_amdgcn_global_load_lds((const unsigned*)((const char*)(gbase) + (voff)[_i]), (PG8_LAS unsigned*)(lds + (bufoff) + ldsw + _i * 8192), 16, 0, 0); } while (0)
; #define PG8_LDA(dst, b, h) do { _Pragma("unroll") for (int m = 0; m < 4; ++m) _Pragma("unroll") for (int k = 0; k < 2; ++k) dst[m][k] = *(const PG8_LAS bf16x8*)(lds + PG8_SA(b, h) + aoff + m * 2048 + k * 1024); } while (0)
; #define PG8_LDB(dst, b, h) do { _Pragma("unroll") for (int n = 0; n < 2; ++n) _Pragma("unroll") for (int k = 0; k < 2; ++k) dst[n][k] = *(const PG8_LAS bf16x8*)(lds + PG8_SB(b, h) + boff + n * 2048 + k * 1024); } while (0)
; #define PG8_MMA(ai, bj, At, Bt) do { __builtin_amdgcn_s_setprio(1); _Pragma("unroll") for (int m = 0; m < 4; ++m) _Pragma("unroll") for (int n = 0; n < 2; ++n) _Pragma("unroll") for (int k = 0; k < 2; ++k) \
;         acc[ai][bj][m][n] = __builtin_amdgcn_mfma_f32_16x16x32_bf16(Bt[n][k], At[m][k], acc[ai][bj][m][n], 0, 0, 0); __builtin_amdgcn_s_setprio(0); } while (0)
; #define PG8_WAIT_V(n) asm volatile("s_waitcnt vmcnt(" #n ")" ::: "memory")
; #define PG8_WAIT_L(n) asm volatile("s_waitcnt lgkmcnt(" #n ")" ::: "memory")
; #define PG8_BAR __builtin_amdgcn_s_barrier()
; #define PG8_SCHED __builtin_amdgcn_sched_barrier(0)
; template <class Epi, class Sched, bool ALIGN_EPI = false, bool SP2 = false>
; __device__ __forceinline__ void gemm_phase(PG8_LAS unsigned char* lds, const Gemm g, const Sched& S, const Epi& E) {
;     ...
;             PG8_WAIT_V(8); PG8_WAIT_L(0); PG8_BAR; PG8_MMA(1, 0, At, B0); PG8_MMA(1, 1, At, B1); PG8_BAR; PG8_SCHED;
;             PG8_LDB(B0, 1, 0); PG8_LDB(B1, 1, 1); PG8_SCHED; PG8_LDA(At, 1, 0); PG8_STAGE(PG8_SA(0, 1), a2 + hstep, voffA);
;             PG8_WAIT_V(8); PG8_WAIT_L(0); PG8_BAR; PG8_MMA(0, 0, At, B0); PG8_MMA(0, 1, At, B1); PG8_BAR; PG8_SCHED;
;             PG8_LDA(At, 1, 1); PG8_STAGE(PG8_SB(1, 0), b3, voffB); PG8_STAGE(PG8_SB(1, 1), b3 + hstep, voffB); PG8_STAGE(PG8_SA(1, 0), a3, voffA);
	s_setprio 1
	s_waitcnt lgkmcnt(0)
	v_mfma_f32_16x16x32_bf16 v[62:65], v[146:149], v[216:219], 0
	v_mfma_f32_16x16x32_bf16 v[58:61], v[156:159], v[216:219], 0
	v_mfma_f32_16x16x32_bf16 v[46:49], v[146:149], v[224:227], 0
	v_mfma_f32_16x16x32_bf16 v[42:45], v[156:159], v[224:227], 0
	v_mfma_f32_16x16x32_bf16 v[30:33], v[146:149], v[232:235], 0
	v_mfma_f32_16x16x32_bf16 v[26:29], v[156:159], v[232:235], 0
	v_mfma_f32_16x16x32_bf16 v[14:17], v[146:149], v[240:243], 0
	v_mfma_f32_16x16x32_bf16 v[10:13], v[156:159], v[240:243], 0
	v_mfma_f32_16x16x32_bf16 v[62:65], v[150:153], v[220:223], v[62:65]
	v_mfma_f32_16x16x32_bf16 v[58:61], v[180:183], v[220:223], v[58:61]
	v_mfma_f32_16x16x32_bf16 v[46:49], v[150:153], v[228:231], v[46:49]
	v_mfma_f32_16x16x32_bf16 v[42:45], v[180:183], v[228:231], v[42:45]
	v_mfma_f32_16x16x32_bf16 v[30:33], v[150:153], v[236:239], v[30:33]
	v_mfma_f32_16x16x32_bf16 v[26:29], v[180:183], v[236:239], v[26:29]
	v_mfma_f32_16x16x32_bf16 v[14:17], v[150:153], v[244:247], v[14:17]
	v_mfma_f32_16x16x32_bf16 v[10:13], v[180:183], v[244:247], v[10:13]
	s_setprio 0
	s_setprio 1
	v_mfma_f32_16x16x32_bf16 v[54:57], v[200:203], v[216:219], 0
	v_mfma_f32_16x16x32_bf16 v[50:53], v[208:211], v[216:219], 0
	v_mfma_f32_16x16x32_bf16 v[38:41], v[200:203], v[224:227], 0
	v_mfma_f32_16x16x32_bf16 v[34:37], v[208:211], v[224:227], 0
	v_mfma_f32_16x16x32_bf16 v[22:25], v[200:203], v[232:235], 0
	v_mfma_f32_16x16x32_bf16 v[18:21], v[208:211], v[232:235], 0
	v_mfma_f32_16x16x32_bf16 v[6:9], v[200:203], v[240:243], 0
	v_mfma_f32_16x16x32_bf16 v[2:5], v[208:211], v[240:243], 0
	v_mfma_f32_16x16x32_bf16 v[54:57], v[204:207], v[220:223], v[54:57]
	v_mfma_f32_16x16x32_bf16 v[50:53], v[212:215], v[220:223], v[50:53]
	v_mfma_f32_16x16x32_bf16 v[38:41], v[204:207], v[228:231], v[38:41]
	v_mfma_f32_16x16x32_bf16 v[34:37], v[212:215], v[228:231], v[34:37]
	v_mfma_f32_16x16x32_bf16 v[22:25], v[204:207], v[236:239], v[22:25]
	v_mfma_f32_16x16x32_bf16 v[18:21], v[212:215], v[236:239], v[18:21]
	v_mfma_f32_16x16x32_bf16 v[6:9], v[204:207], v[244:247], v[6:9]
	v_mfma_f32_16x16x32_bf16 v[2:5], v[212:215], v[244:247], v[2:5]
	s_setprio 0
	s_barrier
	s_add_i32 s48, 0, 0x18000
	v_add_u32_e32 v162, s48, v144
	s_add_i32 s49, 0, 0x1c000
	ds_read_b128 v[146:149], v162
	ds_read_b128 v[150:153], v162 offset:1024
	ds_read_b128 v[156:159], v162 offset:2048
	ds_read_b128 v[180:183], v162 offset:3072
	v_add_u32_e32 v162, s49, v144
	ds_read_b128 v[200:203], v162
	ds_read_b128 v[204:207], v162 offset:1024
	ds_read_b128 v[208:211], v162 offset:2048
	ds_read_b128 v[212:215], v162 offset:3072
	s_add_u32 s18, s18, 0x80000
	s_addc_u32 s19, s19, 0
	s_mov_b32 m0, s33
	ds_read_b128 v[216:219], v145 offset:32768
	ds_read_b128 v[220:223], v145 offset:33792
	ds_read_b128 v[224:227], v145 offset:34816
	ds_read_b128 v[228:231], v145 offset:35840
	ds_read_b128 v[232:235], v145 offset:36864
	ds_read_b128 v[236:239], v145 offset:37888
	ds_read_b128 v[240:243], v145 offset:38912
	ds_read_b128 v[244:247], v145 offset:39936
	global_load_lds_dwordx4 v134, s[18:19]
	s_mov_b32 m0, s34
	s_nop 0
	global_load_lds_dwordx4 v132, s[18:19]
	s_waitcnt vmcnt(8)
	s_waitcnt lgkmcnt(0)
	s_barrier
	s_setprio 1
	s_waitcnt lgkmcnt(0)
	v_mfma_f32_16x16x32_bf16 v[126:129], v[146:149], v[216:219], v[126:129]
	v_mfma_f32_16x16x32_bf16 v[122:125], v[156:159], v[216:219], v[122:125]
	v_mfma_f32_16x16x32_bf16 v[110:113], v[146:149], v[224:227], v[110:113]
	v_mfma_f32_16x16x32_bf16 v[106:109], v[156:159], v[224:227], v[106:109]
	v_mfma_f32_16x16x32_bf16 v[94:97], v[146:149], v[232:235], v[94:97]
	v_mfma_f32_16x16x32_bf16 v[90:93], v[156:159], v[232:235], v[90:93]
	v_mfma_f32_16x16x32_bf16 v[78:81], v[146:149], v[240:243], v[78:81]
	v_mfma_f32_16x16x32_bf16 v[74:77], v[156:159], v[240:243], v[74:77]
	v_mfma_f32_16x16x32_bf16 v[126:129], v[150:153], v[220:223], v[126:129]
	v_mfma_f32_16x16x32_bf16 v[122:125], v[180:183], v[220:223], v[122:125]
	v_mfma_f32_16x16x32_bf16 v[110:113], v[150:153], v[228:231], v[110:113]
	v_mfma_f32_16x16x32_bf16 v[106:109], v[180:183], v[228:231], v[106:109]
	v_mfma_f32_16x16x32_bf16 v[94:97], v[150:153], v[236:239], v[94:97]
	v_mfma_f32_16x16x32_bf16 v[90:93], v[180:183], v[236:239], v[90:93]
	v_mfma_f32_16x16x32_bf16 v[78:81], v[150:153], v[244:247], v[78:81]
	v_mfma_f32_16x16x32_bf16 v[74:77], v[180:183], v[244:247], v[74:77]
	s_setprio 0
	s_setprio 1
	v_mfma_f32_16x16x32_bf16 v[118:121], v[200:203], v[216:219], v[118:121]
	v_mfma_f32_16x16x32_bf16 v[114:117], v[208:211], v[216:219], v[114:117]
	v_mfma_f32_16x16x32_bf16 v[102:105], v[200:203], v[224:227], v[102:105]
	v_mfma_f32_16x16x32_bf16 v[98:101], v[208:211], v[224:227], v[98:101]
	v_mfma_f32_16x16x32_bf16 v[86:89], v[200:203], v[232:235], v[86:89]
	v_mfma_f32_16x16x32_bf16 v[82:85], v[208:211], v[232:235], v[82:85]
	v_mfma_f32_16x16x32_bf16 v[70:73], v[200:203], v[240:243], v[70:73]
	v_mfma_f32_16x16x32_bf16 v[66:69], v[208:211], v[240:243], v[66:69]
	v_mfma_f32_16x16x32_bf16 v[118:121], v[204:207], v[220:223], v[118:121]
	v_mfma_f32_16x16x32_bf16 v[114:117], v[212:215], v[220:223], v[114:117]
	v_mfma_f32_16x16x32_bf16 v[102:105], v[204:207], v[228:231], v[102:105]
	v_mfma_f32_16x16x32_bf16 v[98:101], v[212:215], v[228:231], v[98:101]
	v_mfma_f32_16x16x32_bf16 v[86:89], v[204:207], v[236:239], v[86:89]
	v_mfma_f32_16x16x32_bf16 v[82:85], v[212:215], v[236:239], v[82:85]
	v_mfma_f32_16x16x32_bf16 v[70:73], v[204:207], v[244:247], v[70:73]
	v_mfma_f32_16x16x32_bf16 v[66:69], v[212:215], v[244:247], v[66:69]
	s_setprio 0
	s_barrier
; #define PG8_STAGE(bufoff, gbase, voff) do { _Pragma("unroll") for (int _i = 0; _i < 2; ++_i) \
;         __builtin_amdgcn_global_load_lds((const unsigned*)((const char*)(gbase) + (voff)[_i]), (PG8_LAS unsigned*)(lds + (bufoff) + ldsw + _i * 8192), 16, 0, 0); } while (0)
; #define PG8_LDA(dst, b, h) do { _Pragma("unroll") for (int m = 0; m < 4; ++m) _Pragma("unroll") for (int k = 0; k < 2; ++k) dst[m][k] = *(const PG8_LAS bf16x8*)(lds + PG8_SA(b, h) + aoff + m * 2048 + k * 1024); } while (0)
; #define PG8_MMA(ai, bj, At, Bt) do { __builtin_amdgcn_s_setprio(1); _Pragma("unroll") for (int m = 0; m < 4; ++m) _Pragma("unroll") for (int n = 0; n < 2; ++n) _Pragma("unroll") for (int k = 0; k < 2; ++k) \
;         acc[ai][bj][m][n] = __builtin_amdgcn_mfma_f32_16x16x32_bf16(Bt[n][k], At[m][k], acc[ai][bj][m][n], 0, 0, 0); __builtin_amdgcn_s_setprio(0); } while (0)
; #define PG8_WAIT_V(n) asm volatile("s_waitcnt vmcnt(" #n ")" ::: "memory")
; #define PG8_WAIT_L(n) asm volatile("s_waitcnt lgkmcnt(" #n ")" ::: "memory")
; #define PG8_BAR __builtin_amdgcn_s_barrier()
; #define PG8_SCHED __builtin_amdgcn_sched_barrier(0)
; template <class Epi, class Sched, bool ALIGN_EPI = false, bool SP2 = false>
; __device__ __forceinline__ void gemm_phase(PG8_LAS unsigned char* lds, const Gemm g, const Sched& S, const Epi& E) {
;     ...
;         for (int t = 0; t < nt; t += 2) {
;     ...
;             PG8_LDA(At, 1, 1); PG8_STAGE(PG8_SB(1, 0), b3, voffB); PG8_STAGE(PG8_SB(1, 1), b3 + hstep, voffB); PG8_STAGE(PG8_SA(1, 0), a3, voffA);
;             PG8_WAIT_V(8); PG8_WAIT_L(0); PG8_BAR; PG8_MMA(1, 0, At, B0); PG8_MMA(1, 1, At, B1); PG8_BAR; PG8_SCHED;
	s_add_i32 s18, s48, s29
	s_mov_b32 m0, s18
	ds_read_b128 v[216:219], v145 offset:49152
	ds_read_b128 v[220:223], v145 offset:50176
	ds_read_b128 v[224:227], v145 offset:51200
	ds_read_b128 v[228:231], v145 offset:52224
	ds_read_b128 v[232:235], v145 offset:53248
	ds_read_b128 v[236:239], v145 offset:54272
	ds_read_b128 v[240:243], v145 offset:55296
	ds_read_b128 v[244:247], v145 offset:56320
	global_load_lds_dwordx4 v0, s[84:85]
	s_add_i32 m0, s18, 0x2000
	s_add_u32 s16, s16, 0x80080
	s_addc_u32 s17, s17, 0
	s_add_i32 s18, s49, s29
	global_load_lds_dwordx4 v130, s[84:85]
	s_mov_b32 m0, s18
	s_nop 0
	global_load_lds_dwordx4 v0, s[16:17]
	s_add_i32 m0, s18, 0x2000
	s_nop 0
	global_load_lds_dwordx4 v130, s[16:17]
	s_mov_b32 m0, s35
	s_nop 0
	global_load_lds_dwordx4 v134, s[86:87]
	s_mov_b32 m0, s36
	s_nop 0
	global_load_lds_dwordx4 v132, s[86:87]
	s_waitcnt vmcnt(8)
	s_waitcnt lgkmcnt(0)
	s_barrier
	s_setprio 1
	s_waitcnt lgkmcnt(0)
	v_mfma_f32_16x16x32_bf16 v[62:65], v[146:149], v[216:219], v[62:65]
	v_mfma_f32_16x16x32_bf16 v[58:61], v[156:159], v[216:219], v[58:61]
	v_mfma_f32_16x16x32_bf16 v[46:49], v[146:149], v[224:227], v[46:49]
	v_mfma_f32_16x16x32_bf16 v[42:45], v[156:159], v[224:227], v[42:45]
	v_mfma_f32_16x16x32_bf16 v[30:33], v[146:149], v[232:235], v[30:33]
	v_mfma_f32_16x16x32_bf16 v[26:29], v[156:159], v[232:235], v[26:29]
	v_mfma_f32_16x16x32_bf16 v[14:17], v[146:149], v[240:243], v[14:17]
	v_mfma_f32_16x16x32_bf16 v[10:13], v[156:159], v[240:243], v[10:13]
	v_mfma_f32_16x16x32_bf16 v[62:65], v[150:153], v[220:223], v[62:65]
	v_mfma_f32_16x16x32_bf16 v[58:61], v[180:183], v[220:223], v[58:61]
	v_mfma_f32_16x16x32_bf16 v[46:49], v[150:153], v[228:231], v[46:49]
	v_mfma_f32_16x16x32_bf16 v[42:45], v[180:183], v[228:231], v[42:45]
	v_mfma_f32_16x16x32_bf16 v[30:33], v[150:153], v[236:239], v[30:33]
	v_mfma_f32_16x16x32_bf16 v[26:29], v[180:183], v[236:239], v[26:29]
	v_mfma_f32_16x16x32_bf16 v[14:17], v[150:153], v[244:247], v[14:17]
	v_mfma_f32_16x16x32_bf16 v[10:13], v[180:183], v[244:247], v[10:13]
	s_setprio 0
	s_setprio 1
	v_mfma_f32_16x16x32_bf16 v[54:57], v[200:203], v[216:219], v[54:57]
	v_mfma_f32_16x16x32_bf16 v[50:53], v[208:211], v[216:219], v[50:53]
	v_mfma_f32_16x16x32_bf16 v[38:41], v[200:203], v[224:227], v[38:41]
	v_mfma_f32_16x16x32_bf16 v[34:37], v[208:211], v[224:227], v[34:37]
	v_mfma_f32_16x16x32_bf16 v[22:25], v[200:203], v[232:235], v[22:25]
	v_mfma_f32_16x16x32_bf16 v[18:21], v[208:211], v[232:235], v[18:21]
	v_mfma_f32_16x16x32_bf16 v[6:9], v[200:203], v[240:243], v[6:9]
	v_mfma_f32_16x16x32_bf16 v[2:5], v[208:211], v[240:243], v[2:5]
	v_mfma_f32_16x16x32_bf16 v[54:57], v[204:207], v[220:223], v[54:57]
	v_mfma_f32_16x16x32_bf16 v[50:53], v[212:215], v[220:223], v[50:53]
	v_mfma_f32_16x16x32_bf16 v[38:41], v[204:207], v[228:231], v[38:41]
	v_mfma_f32_16x16x32_bf16 v[34:37], v[212:215], v[228:231], v[34:37]
	v_mfma_f32_16x16x32_bf16 v[22:25], v[204:207], v[236:239], v[22:25]
	v_mfma_f32_16x16x32_bf16 v[18:21], v[212:215], v[236:239], v[18:21]
	v_mfma_f32_16x16x32_bf16 v[6:9], v[204:207], v[244:247], v[6:9]
	v_mfma_f32_16x16x32_bf16 v[2:5], v[212:215], v[244:247], v[2:5]
	s_setprio 0
	s_barrier
	s_add_i32 s47, s47, 2
	s_add_u32 s14, s14, 0x100
	s_addc_u32 s15, s15, 0
	s_cmp_gt_u32 s47, 29

; #define PG8_STAGE(bufoff, gbase, voff) do { _Pragma("unroll") for (int _i = 0; _i < 2; ++_i) \
;         __builtin_amdgcn_global_load_lds((const unsigned*)((const char*)(gbase) + (voff)[_i]), (PG8_LAS unsigned*)(lds + (bufoff) + ldsw + _i * 8192), 16, 0, 0); } while (0)
; #define PG8_WAIT_V(n) asm volatile("s_waitcnt vmcnt(" #n ")" ::: "memory")
; #define PG8_BAR __builtin_amdgcn_s_barrier()
; template <class Epi, class Sched, bool ALIGN_EPI = false, bool SP2 = false>
; __device__ __forceinline__ void gemm_phase(PG8_LAS unsigned char* lds, const Gemm g, const Sched& S, const Epi& E) {
;     ...
;     for (int i = 0; i < 2; ++i) { int R, C; stage_rc(tid * 16 + i * 8192, R, C); const int Rb = Epi::PERM ? ((R & ~31) + perm32(R & 31)) : R;
;         voffA[i] = (unsigned)(R * K + C) * 2u; voffB[i] = (unsigned)(Rb * K + C) * 2u; }
;     const size_t kstep = (size_t)(BK * 2);
;     const size_t hstep = (size_t)HALF * K * 2;
;     const size_t tstep = 2 * hstep;
;     const unsigned ldsw = (unsigned)wid * 1024u;
;     const int aoff = lds_byte(wr * 64 + fr, fq * 8), boff = lds_byte(wc * 32 + fr, fq * 8);
;     ...
;     f32x4 acc[2][2][4][2];
; #pragma unroll
;     for (int a = 0; a < 2; ++a)
; #pragma unroll
;         for (int b = 0; b < 2; ++b)
; #pragma unroll
;             for (int m = 0; m < 4; ++m)
; #pragma unroll
;                 for (int n = 0; n < 2; ++n) acc[a][b][m][n] = (f32x4){0.f, 0.f, 0.f, 0.f};
;     bf16x8 At[4][2], B0[2][2], B1[2][2];
;     const char* cA = (const char*)g.A + (size_t)cur.pm * tstep; const char* cB = (const char*)g.Bt + (size_t)cur.pn * tstep;
;     S.a_ready(cur);
;     if constexpr (SP2) {
;         PG8_STAGE(PG8_SB(0, 0), cB, voffB); PG8_STAGE(PG8_SB(0, 1), cB + hstep, voffB); PG8_STAGE(PG8_SA(0, 0), cA, voffA); PG8_STAGE(PG8_SA(0, 1), cA + hstep, voffA);
;         if (wr == 1) PG8_BAR;
;         PG8_WAIT_V(2); PG8_BAR;
;         PG8_STAGE(PG8_SB(1, 0), cB + kstep, voffB); PG8_STAGE(PG8_SA(1, 0), cA + kstep, voffA); PG8_STAGE(PG8_SB(1, 1), cB + hstep + kstep, voffB);
;         PG8_WAIT_V(6); PG8_BAR;
.LBB0_1052:
	v_and_b32_e32 v178, 15, v154
	v_lshl_add_u64 v[10:11], s[10:11], 0, v[0:1]
	v_mov_b32_e32 v131, v1
	v_readlane_b32 s6, v254, 8
	v_lshlrev_b32_e32 v155, 6, v178
	v_lshlrev_b32_e32 v19, 2, v154
	v_lshl_add_u64 v[12:13], s[10:11], 0, v[130:131]
	v_mov_b32_e32 v135, v1
	v_readlane_b32 s7, v254, 9
	s_and_b32 s22, s18, 3
	s_lshl_b32 s0, s19, 13
	v_and_or_b32 v18, v154, 48, v155
	v_and_b32_e32 v19, 32, v19
	s_add_i32 m0, s26, 0x18000
	v_lshl_add_u64 v[10:11], v[10:11], 0, s[44:45]
	v_lshl_add_u64 v[14:15], s[6:7], 0, v[134:135]
	v_mov_b32_e32 v133, v1
	s_lshl_b32 s16, s19, 6
	v_bitop3_b32 v20, v18, s0, v19 bitop3:0xde
	s_lshl_b32 s0, s22, 12
	s_waitcnt vmcnt(2)
	s_barrier
	global_load_lds_dwordx4 v[10:11], off
	v_lshl_add_u64 v[10:11], v[12:13], 0, s[44:45]
	s_add_i32 m0, s26, 0x1a000
	s_add_i32 s30, s26, 0x8000
	s_add_i32 s31, s26, 0xa000
	v_lshl_add_u64 v[16:17], s[6:7], 0, v[132:133]
	v_bitop3_b32 v144, v18, s0, v19 bitop3:0xde
	global_load_lds_dwordx4 v[10:11], off
	v_lshl_add_u64 v[10:11], v[14:15], 0, s[44:45]
	s_mov_b32 m0, s30
	s_add_u32 s0, s10, 0x160080
	global_load_lds_dwordx4 v[10:11], off
	v_lshl_add_u64 v[10:11], v[16:17], 0, s[44:45]
	s_mov_b32 m0, s31
	s_addc_u32 s1, s11, 0
	global_load_lds_dwordx4 v[10:11], off
	s_add_i32 m0, s26, 0x1c000
	v_lshl_add_u64 v[10:11], s[0:1], 0, v[0:1]
	global_load_lds_dwordx4 v[10:11], off
	v_lshl_add_u64 v[10:11], s[0:1], 0, v[130:131]
	s_add_i32 m0, s26, 0x1e000
	s_movk_i32 s3, 0x1600
	global_load_lds_dwordx4 v[10:11], off
	v_lshrrev_b32_e32 v7, 1, v7
	v_mul_lo_u32 v6, v6, s3
	s_mov_b32 s2, 0x16000
	v_mad_u64_u32 v[6:7], s[0:1], v7, s2, v[6:7]
	v_or_b32_e32 v6, v6, v8
	v_add_lshl_u32 v136, v6, v9, 1
	v_lshrrev_b32_e32 v6, 1, v2
	v_mul_lo_u32 v2, v3, s3
	v_mad_u64_u32 v[2:3], s[0:1], v6, s2, v[2:3]
	s_waitcnt vmcnt(6)
	v_or_b32_e32 v2, v2, v4
	v_add_lshl_u32 v138, v2, v5, 1
	v_readlane_b32 s0, v254, 4
	v_mov_b32_e32 v137, v1
	v_mov_b32_e32 v139, v1
	s_mov_b32 s33, 0
	v_add_u32_e32 v145, 0, v20
	v_readlane_b32 s21, v253, 49
	s_mov_b32 s20, s0
	s_barrier
	v_readlane_b32 s1, v254, 5
	s_branch .LBB0_1055

;     __device__ bool next(int i, Unit& u) const { const int j = first + i * G; if (j >= count) return false; u.pm = j / nN; u.pn = j % nN; return true; }
; #define PG8_STAGE(bufoff, gbase, voff) do { _Pragma("unroll") for (int _i = 0; _i < 2; ++_i) \
;         __builtin_amdgcn_global_load_lds((const unsigned*)((const char*)(gbase) + (voff)[_i]), (PG8_LAS unsigned*)(lds + (bufoff) + ldsw + _i * 8192), 16, 0, 0); } while (0)
; #define PG8_LDA(dst, b, h) do { _Pragma("unroll") for (int m = 0; m < 4; ++m) _Pragma("unroll") for (int k = 0; k < 2; ++k) dst[m][k] = *(const PG8_LAS bf16x8*)(lds + PG8_SA(b, h) + aoff + m * 2048 + k * 1024); } while (0)
; #define PG8_LDB(dst, b, h) do { _Pragma("unroll") for (int n = 0; n < 2; ++n) _Pragma("unroll") for (int k = 0; k < 2; ++k) dst[n][k] = *(const PG8_LAS bf16x8*)(lds + PG8_SB(b, h) + boff + n * 2048 + k * 1024); } while (0)
; #define PG8_WAIT_V(n) asm volatile("s_waitcnt vmcnt(" #n ")" ::: "memory")
; #define PG8_BAR __builtin_amdgcn_s_barrier()
; template <class Epi, class Sched, bool ALIGN_EPI = false, bool SP2 = false>
; __device__ __forceinline__ void gemm_phase(PG8_LAS unsigned char* lds, const Gemm g, const Sched& S, const Epi& E) {
;     ...
;         const bool has_next = S.next(ui + 1, nxt);
;         const char* nA = has_next ? (const char*)g.A + (size_t)nxt.pm * tstep : cA; const char* nB = has_next ? (const char*)g.Bt + (size_t)nxt.pn * tstep : cB;
;         for (int t = 0; t < nt; t += 2) {
;             const bool last = (t == nt - 2);
;             const char* a1 = cA + (size_t)(t + 1) * kstep;
;             const char* a2 = last ? nA : cA + (size_t)(t + 2) * kstep; const char* b2 = last ? nB : cB + (size_t)(t + 2) * kstep;
;             const char* a3 = a2 + kstep; const char* b3 = b2 + kstep;
;             if (last && has_next) S.a_ready(nxt);
;             if constexpr (SP2) {
;             PG8_LDB(B0, 0, 0); PG8_LDB(B1, 0, 1); PG8_SCHED; PG8_LDA(At, 0, 0); PG8_STAGE(PG8_SA(1, 1), a1 + hstep, voffA);
;             PG8_WAIT_V(8); PG8_WAIT_L(0); PG8_BAR; PG8_MMA(0, 0, At, B0); PG8_MMA(0, 1, At, B1); PG8_BAR; PG8_SCHED;
;             PG8_LDA(At, 0, 1); PG8_STAGE(PG8_SB(0, 0), b2, voffB); PG8_STAGE(PG8_SB(0, 1), b2 + hstep, voffB); PG8_STAGE(PG8_SA(0, 0), a2, voffA);
;             PG8_WAIT_V(8); PG8_WAIT_L(0); PG8_BAR; PG8_MMA(1, 0, At, B0); PG8_MMA(1, 1, At, B1); PG8_BAR; PG8_SCHED;
.LBB0_1065:
	s_add_u32 s37, s10, 0x100
	s_addc_u32 s38, s11, 0
	s_add_u32 s10, s6, 0x160080
	s_addc_u32 s11, s7, 0
	v_lshl_add_u64 v[140:141], s[10:11], 0, v[136:137]
	v_lshl_add_u64 v[142:143], s[10:11], 0, v[138:139]
	s_mov_b32 s39, -2
	s_mov_b64 s[10:11], 0
	s_add_u32 s12, s6, s10
	s_addc_u32 s13, s7, s11
	s_add_u32 s12, s12, 0x100
	s_addc_u32 s13, s13, 0
	s_add_u32 s40, s37, s10
	s_addc_u32 s41, s38, s11
	s_add_i32 s42, 0, 0x10000
	s_cmpk_eq_i32 s10, 0x2b00
	s_cselect_b32 s15, s9, s13
	s_cselect_b32 s14, s8, s12
	v_add_u32_e32 v160, s42, v144
	s_cselect_b32 s13, s5, s41
	s_cselect_b32 s12, s4, s40
	s_add_i32 s43, 0, 0x14000
	ds_read_b128 v[146:149], v160
	ds_read_b128 v[150:153], v160 offset:1024
	ds_read_b128 v[156:159], v160 offset:2048
	ds_read_b128 v[164:167], v160 offset:3072
	v_add_u32_e32 v160, s43, v144
	ds_read_b128 v[172:175], v160
	ds_read_b128 v[180:183], v160 offset:1024
	ds_read_b128 v[200:203], v160 offset:2048
	ds_read_b128 v[204:207], v160 offset:3072
	v_lshl_add_u64 v[160:161], v[140:141], 0, s[10:11]
	s_add_i32 m0, s26, 0xc000
	ds_read_b128 v[208:211], v145
	ds_read_b128 v[212:215], v145 offset:1024
	ds_read_b128 v[216:219], v145 offset:2048
	ds_read_b128 v[220:223], v145 offset:3072
	ds_read_b128 v[224:227], v145 offset:4096
	ds_read_b128 v[228:231], v145 offset:5120
	ds_read_b128 v[232:235], v145 offset:6144
	ds_read_b128 v[236:239], v145 offset:7168
	global_load_lds_dwordx4 v[160:161], off
	v_lshl_add_u64 v[160:161], v[142:143], 0, s[10:11]
	s_add_i32 m0, s26, 0xe000
	s_nop 0
	global_load_lds_dwordx4 v[160:161], off
	s_waitcnt vmcnt(8)
	s_waitcnt lgkmcnt(0)
	s_barrier
	s_setprio 1
	s_waitcnt lgkmcnt(0)
	v_mfma_f32_16x16x32_bf16 v[126:129], v[146:149], v[208:211], 0
	v_mfma_f32_16x16x32_bf16 v[122:125], v[156:159], v[208:211], 0
	v_mfma_f32_16x16x32_bf16 v[110:113], v[146:149], v[216:219], 0
	v_mfma_f32_16x16x32_bf16 v[106:109], v[156:159], v[216:219], 0
	v_mfma_f32_16x16x32_bf16 v[94:97], v[146:149], v[224:227], 0
	v_mfma_f32_16x16x32_bf16 v[90:93], v[156:159], v[224:227], 0
	v_mfma_f32_16x16x32_bf16 v[78:81], v[146:149], v[232:235], 0
	v_mfma_f32_16x16x32_bf16 v[74:77], v[156:159], v[232:235], 0
	v_mfma_f32_16x16x32_bf16 v[126:129], v[150:153], v[212:215], v[126:129]
	v_mfma_f32_16x16x32_bf16 v[122:125], v[164:167], v[212:215], v[122:125]
	v_mfma_f32_16x16x32_bf16 v[110:113], v[150:153], v[220:223], v[110:113]
	v_mfma_f32_16x16x32_bf16 v[106:109], v[164:167], v[220:223], v[106:109]
	v_mfma_f32_16x16x32_bf16 v[94:97], v[150:153], v[228:231], v[94:97]
	v_mfma_f32_16x16x32_bf16 v[90:93], v[164:167], v[228:231], v[90:93]
	v_mfma_f32_16x16x32_bf16 v[78:81], v[150:153], v[236:239], v[78:81]
	v_mfma_f32_16x16x32_bf16 v[74:77], v[164:167], v[236:239], v[74:77]
	s_setprio 0
	s_setprio 1
	v_mfma_f32_16x16x32_bf16 v[118:121], v[172:175], v[208:211], 0
	v_mfma_f32_16x16x32_bf16 v[114:117], v[200:203], v[208:211], 0
	v_mfma_f32_16x16x32_bf16 v[102:105], v[172:175], v[216:219], 0
	v_mfma_f32_16x16x32_bf16 v[98:101], v[200:203], v[216:219], 0
	v_mfma_f32_16x16x32_bf16 v[86:89], v[172:175], v[224:227], 0
	v_mfma_f32_16x16x32_bf16 v[82:85], v[200:203], v[224:227], 0
	v_mfma_f32_16x16x32_bf16 v[70:73], v[172:175], v[232:235], 0
	v_mfma_f32_16x16x32_bf16 v[66:69], v[200:203], v[232:235], 0
	v_mfma_f32_16x16x32_bf16 v[118:121], v[180:183], v[212:215], v[118:121]
	v_mfma_f32_16x16x32_bf16 v[114:117], v[204:207], v[212:215], v[114:117]
	v_mfma_f32_16x16x32_bf16 v[102:105], v[180:183], v[220:223], v[102:105]
	v_mfma_f32_16x16x32_bf16 v[98:101], v[204:207], v[220:223], v[98:101]
	v_mfma_f32_16x16x32_bf16 v[86:89], v[180:183], v[228:231], v[86:89]
	v_mfma_f32_16x16x32_bf16 v[82:85], v[204:207], v[228:231], v[82:85]
	v_mfma_f32_16x16x32_bf16 v[70:73], v[180:183], v[236:239], v[70:73]
	v_mfma_f32_16x16x32_bf16 v[66:69], v[204:207], v[236:239], v[66:69]
	s_setprio 0
	s_barrier
	s_add_i32 s40, s42, s25
	s_add_u32 s84, s12, s44
	s_addc_u32 s85, s13, s45
	s_mov_b32 m0, s40
	ds_read_b128 v[208:211], v145 offset:16384
	ds_read_b128 v[212:215], v145 offset:17408
	ds_read_b128 v[216:219], v145 offset:18432
	ds_read_b128 v[220:223], v145 offset:19456
	ds_read_b128 v[224:227], v145 offset:20480
	ds_read_b128 v[228:231], v145 offset:21504
	ds_read_b128 v[232:235], v145 offset:22528
	ds_read_b128 v[236:239], v145 offset:23552
	global_load_lds_dwordx4 v0, s[12:13]
	s_add_i32 m0, s40, 0x2000
	s_add_u32 s40, s12, 0x160000
	s_addc_u32 s41, s13, 0
	s_add_i32 s42, s43, s25
	global_load_lds_dwordx4 v130, s[12:13]
	s_mov_b32 m0, s42
	s_nop 0
	global_load_lds_dwordx4 v0, s[40:41]
	s_add_i32 m0, s42, 0x2000
	s_nop 0
	global_load_lds_dwordx4 v130, s[40:41]
	s_add_u32 s86, s14, s44
	s_addc_u32 s87, s15, s45
	s_mov_b32 m0, s26
	s_nop 0
	global_load_lds_dwordx4 v134, s[14:15]
	s_mov_b32 m0, s27
	s_nop 0
	global_load_lds_dwordx4 v132, s[14:15]
	s_waitcnt vmcnt(8)
	s_waitcnt lgkmcnt(0)
	s_barrier
; #define PG8_STAGE(bufoff, gbase, voff) do { _Pragma("unroll") for (int _i = 0; _i < 2; ++_i) \
;         __builtin_amdgcn_global_load_lds((const unsigned*)((const char*)(gbase) + (voff)[_i]), (PG8_LAS unsigned*)(lds + (bufoff) + ldsw + _i * 8192), 16, 0, 0); } while (0)
; #define PG8_LDA(dst, b, h) do { _Pragma("unroll") for (int m = 0; m < 4; ++m) _Pragma("unroll") for (int k = 0; k < 2; ++k) dst[m][k] = *(const PG8_LAS bf16x8*)(lds + PG8_SA(b, h) + aoff + m * 2048 + k * 1024); } while (0)
; #define PG8_LDB(dst, b, h) do { _Pragma("unroll") for (int n = 0; n < 2; ++n) _Pragma("unroll") for (int k = 0; k < 2; ++k) dst[n][k] = *(const PG8_LAS bf16x8*)(lds + PG8_SB(b, h) + boff + n * 2048 + k * 1024); } while (0)
; #define PG8_MMA(ai, bj, At, Bt) do { __builtin_amdgcn_s_setprio(1); _Pragma("unroll") for (int m = 0; m < 4; ++m) _Pragma("unroll") for (int n = 0; n < 2; ++n) _Pragma("unroll") for (int k = 0; k < 2; ++k) \
;         acc[ai][bj][m][n] = __builtin_amdgcn_mfma_f32_16x16x32_bf16(Bt[n][k], At[m][k], acc[ai][bj][m][n], 0, 0, 0); __builtin_amdgcn_s_setprio(0); } while (0)
; #define PG8_WAIT_V(n) asm volatile("s_waitcnt vmcnt(" #n ")" ::: "memory")
; #define PG8_WAIT_L(n) asm volatile("s_waitcnt lgkmcnt(" #n ")" ::: "memory")
; #define PG8_BAR __builtin_amdgcn_s_barrier()
; #define PG8_SCHED __builtin_amdgcn_sched_barrier(0)
; template <class Epi, class Sched, bool ALIGN_EPI = false, bool SP2 = false>
; __device__ __forceinline__ void gemm_phase(PG8_LAS unsigned char* lds, const Gemm g, const Sched& S, const Epi& E) {
;     ...
;             PG8_WAIT_V(8); PG8_WAIT_L(0); PG8_BAR; PG8_MMA(1, 0, At, B0); PG8_MMA(1, 1, At, B1); PG8_BAR; PG8_SCHED;
;             PG8_LDB(B0, 1, 0); PG8_LDB(B1, 1, 1); PG8_SCHED; PG8_LDA(At, 1, 0); PG8_STAGE(PG8_SA(0, 1), a2 + hstep, voffA);
;             PG8_WAIT_V(8); PG8_WAIT_L(0); PG8_BAR; PG8_MMA(0, 0, At, B0); PG8_MMA(0, 1, At, B1); PG8_BAR; PG8_SCHED;
;             PG8_LDA(At, 1, 1); PG8_STAGE(PG8_SB(1, 0), b3, voffB); PG8_STAGE(PG8_SB(1, 1), b3 + hstep, voffB); PG8_STAGE(PG8_SA(1, 0), a3, voffA);
	s_setprio 1
	s_waitcnt lgkmcnt(0)
	v_mfma_f32_16x16x32_bf16 v[62:65], v[146:149], v[208:211], 0
	v_mfma_f32_16x16x32_bf16 v[58:61], v[156:159], v[208:211], 0
	v_mfma_f32_16x16x32_bf16 v[46:49], v[146:149], v[216:219], 0
	v_mfma_f32_16x16x32_bf16 v[42:45], v[156:159], v[216:219], 0
	v_mfma_f32_16x16x32_bf16 v[30:33], v[146:149], v[224:227], 0
	v_mfma_f32_16x16x32_bf16 v[26:29], v[156:159], v[224:227], 0
	v_mfma_f32_16x16x32_bf16 v[14:17], v[146:149], v[232:235], 0
	v_mfma_f32_16x16x32_bf16 v[10:13], v[156:159], v[232:235], 0
	v_mfma_f32_16x16x32_bf16 v[62:65], v[150:153], v[212:215], v[62:65]
	v_mfma_f32_16x16x32_bf16 v[58:61], v[164:167], v[212:215], v[58:61]
	v_mfma_f32_16x16x32_bf16 v[46:49], v[150:153], v[220:223], v[46:49]
	v_mfma_f32_16x16x32_bf16 v[42:45], v[164:167], v[220:223], v[42:45]
	v_mfma_f32_16x16x32_bf16 v[30:33], v[150:153], v[228:231], v[30:33]
	v_mfma_f32_16x16x32_bf16 v[26:29], v[164:167], v[228:231], v[26:29]
	v_mfma_f32_16x16x32_bf16 v[14:17], v[150:153], v[236:239], v[14:17]
	v_mfma_f32_16x16x32_bf16 v[10:13], v[164:167], v[236:239], v[10:13]
	s_setprio 0
	s_setprio 1
	v_mfma_f32_16x16x32_bf16 v[54:57], v[172:175], v[208:211], 0
	v_mfma_f32_16x16x32_bf16 v[50:53], v[200:203], v[208:211], 0
	v_mfma_f32_16x16x32_bf16 v[38:41], v[172:175], v[216:219], 0
	v_mfma_f32_16x16x32_bf16 v[34:37], v[200:203], v[216:219], 0
	v_mfma_f32_16x16x32_bf16 v[22:25], v[172:175], v[224:227], 0
	v_mfma_f32_16x16x32_bf16 v[18:21], v[200:203], v[224:227], 0
	v_mfma_f32_16x16x32_bf16 v[6:9], v[172:175], v[232:235], 0
	v_mfma_f32_16x16x32_bf16 v[2:5], v[200:203], v[232:235], 0
	v_mfma_f32_16x16x32_bf16 v[54:57], v[180:183], v[212:215], v[54:57]
	v_mfma_f32_16x16x32_bf16 v[50:53], v[204:207], v[212:215], v[50:53]
	v_mfma_f32_16x16x32_bf16 v[38:41], v[180:183], v[220:223], v[38:41]
	v_mfma_f32_16x16x32_bf16 v[34:37], v[204:207], v[220:223], v[34:37]
	v_mfma_f32_16x16x32_bf16 v[22:25], v[180:183], v[228:231], v[22:25]
	v_mfma_f32_16x16x32_bf16 v[18:21], v[204:207], v[228:231], v[18:21]
	v_mfma_f32_16x16x32_bf16 v[6:9], v[180:183], v[236:239], v[6:9]
	v_mfma_f32_16x16x32_bf16 v[2:5], v[204:207], v[236:239], v[2:5]
	s_setprio 0
	s_barrier
	s_add_i32 s40, 0, 0x18000
	v_add_u32_e32 v162, s40, v144
	s_add_i32 s41, 0, 0x1c000
	ds_read_b128 v[146:149], v162
	ds_read_b128 v[150:153], v162 offset:1024
	ds_read_b128 v[156:159], v162 offset:2048
	ds_read_b128 v[164:167], v162 offset:3072
	v_add_u32_e32 v162, s41, v144
	ds_read_b128 v[172:175], v162
	ds_read_b128 v[180:183], v162 offset:1024
	ds_read_b128 v[200:203], v162 offset:2048
	ds_read_b128 v[204:207], v162 offset:3072
	s_add_u32 s14, s14, 0x160000
	s_addc_u32 s15, s15, 0
	s_mov_b32 m0, s28
	ds_read_b128 v[208:211], v145 offset:32768
	ds_read_b128 v[212:215], v145 offset:33792
	ds_read_b128 v[216:219], v145 offset:34816
	ds_read_b128 v[220:223], v145 offset:35840
	ds_read_b128 v[224:227], v145 offset:36864
	ds_read_b128 v[228:231], v145 offset:37888
	ds_read_b128 v[232:235], v145 offset:38912
	ds_read_b128 v[236:239], v145 offset:39936
	global_load_lds_dwordx4 v134, s[14:15]
	s_mov_b32 m0, s29
	s_nop 0
	global_load_lds_dwordx4 v132, s[14:15]
	s_waitcnt vmcnt(8)
	s_waitcnt lgkmcnt(0)
	s_barrier
	s_setprio 1
	s_waitcnt lgkmcnt(0)
	v_mfma_f32_16x16x32_bf16 v[126:129], v[146:149], v[208:211], v[126:129]
	v_mfma_f32_16x16x32_bf16 v[122:125], v[156:159], v[208:211], v[122:125]
	v_mfma_f32_16x16x32_bf16 v[110:113], v[146:149], v[216:219], v[110:113]
	v_mfma_f32_16x16x32_bf16 v[106:109], v[156:159], v[216:219], v[106:109]
	v_mfma_f32_16x16x32_bf16 v[94:97], v[146:149], v[224:227], v[94:97]
	v_mfma_f32_16x16x32_bf16 v[90:93], v[156:159], v[224:227], v[90:93]
	v_mfma_f32_16x16x32_bf16 v[78:81], v[146:149], v[232:235], v[78:81]
	v_mfma_f32_16x16x32_bf16 v[74:77], v[156:159], v[232:235], v[74:77]
	v_mfma_f32_16x16x32_bf16 v[126:129], v[150:153], v[212:215], v[126:129]
	v_mfma_f32_16x16x32_bf16 v[122:125], v[164:167], v[212:215], v[122:125]
	v_mfma_f32_16x16x32_bf16 v[110:113], v[150:153], v[220:223], v[110:113]
	v_mfma_f32_16x16x32_bf16 v[106:109], v[164:167], v[220:223], v[106:109]
	v_mfma_f32_16x16x32_bf16 v[94:97], v[150:153], v[228:231], v[94:97]
	v_mfma_f32_16x16x32_bf16 v[90:93], v[164:167], v[228:231], v[90:93]
	v_mfma_f32_16x16x32_bf16 v[78:81], v[150:153], v[236:239], v[78:81]
	v_mfma_f32_16x16x32_bf16 v[74:77], v[164:167], v[236:239], v[74:77]
	s_setprio 0
	s_setprio 1
	v_mfma_f32_16x16x32_bf16 v[118:121], v[172:175], v[208:211], v[118:121]
	v_mfma_f32_16x16x32_bf16 v[114:117], v[200:203], v[208:211], v[114:117]
	v_mfma_f32_16x16x32_bf16 v[102:105], v[172:175], v[216:219], v[102:105]
	v_mfma_f32_16x16x32_bf16 v[98:101], v[200:203], v[216:219], v[98:101]
	v_mfma_f32_16x16x32_bf16 v[86:89], v[172:175], v[224:227], v[86:89]
	v_mfma_f32_16x16x32_bf16 v[82:85], v[200:203], v[224:227], v[82:85]
	v_mfma_f32_16x16x32_bf16 v[70:73], v[172:175], v[232:235], v[70:73]
	v_mfma_f32_16x16x32_bf16 v[66:69], v[200:203], v[232:235], v[66:69]
	v_mfma_f32_16x16x32_bf16 v[118:121], v[180:183], v[212:215], v[118:121]
	v_mfma_f32_16x16x32_bf16 v[114:117], v[204:207], v[212:215], v[114:117]
	v_mfma_f32_16x16x32_bf16 v[102:105], v[180:183], v[220:223], v[102:105]
	v_mfma_f32_16x16x32_bf16 v[98:101], v[204:207], v[220:223], v[98:101]
	v_mfma_f32_16x16x32_bf16 v[86:89], v[180:183], v[228:231], v[86:89]
	v_mfma_f32_16x16x32_bf16 v[82:85], v[204:207], v[228:231], v[82:85]
	v_mfma_f32_16x16x32_bf16 v[70:73], v[180:183], v[236:239], v[70:73]
	v_mfma_f32_16x16x32_bf16 v[66:69], v[204:207], v[236:239], v[66:69]
	s_setprio 0
	s_barrier
; #define PG8_STAGE(bufoff, gbase, voff) do { _Pragma("unroll") for (int _i = 0; _i < 2; ++_i) \
;         __builtin_amdgcn_global_load_lds((const unsigned*)((const char*)(gbase) + (voff)[_i]), (PG8_LAS unsigned*)(lds + (bufoff) + ldsw + _i * 8192), 16, 0, 0); } while (0)
; #define PG8_LDA(dst, b, h) do { _Pragma("unroll") for (int m = 0; m < 4; ++m) _Pragma("unroll") for (int k = 0; k < 2; ++k) dst[m][k] = *(const PG8_LAS bf16x8*)(lds + PG8_SA(b, h) + aoff + m * 2048 + k * 1024); } while (0)
; #define PG8_MMA(ai, bj, At, Bt) do { __builtin_amdgcn_s_setprio(1); _Pragma("unroll") for (int m = 0; m < 4; ++m) _Pragma("unroll") for (int n = 0; n < 2; ++n) _Pragma("unroll") for (int k = 0; k < 2; ++k) \
;         acc[ai][bj][m][n] = __builtin_amdgcn_mfma_f32_16x16x32_bf16(Bt[n][k], At[m][k], acc[ai][bj][m][n], 0, 0, 0); __builtin_amdgcn_s_setprio(0); } while (0)
; #define PG8_WAIT_V(n) asm volatile("s_waitcnt vmcnt(" #n ")" ::: "memory")
; #define PG8_WAIT_L(n) asm volatile("s_waitcnt lgkmcnt(" #n ")" ::: "memory")
; #define PG8_BAR __builtin_amdgcn_s_barrier()
; #define PG8_SCHED __builtin_amdgcn_sched_barrier(0)
; template <class Epi, class Sched, bool ALIGN_EPI = false, bool SP2 = false>
; __device__ __forceinline__ void gemm_phase(PG8_LAS unsigned char* lds, const Gemm g, const Sched& S, const Epi& E) {
;     ...
;         for (int t = 0; t < nt; t += 2) {
;     ...
;             PG8_LDA(At, 1, 1); PG8_STAGE(PG8_SB(1, 0), b3, voffB); PG8_STAGE(PG8_SB(1, 1), b3 + hstep, voffB); PG8_STAGE(PG8_SA(1, 0), a3, voffA);
;             PG8_WAIT_V(8); PG8_WAIT_L(0); PG8_BAR; PG8_MMA(1, 0, At, B0); PG8_MMA(1, 1, At, B1); PG8_BAR; PG8_SCHED;
	s_add_i32 s14, s40, s25
	s_mov_b32 m0, s14
	ds_read_b128 v[208:211], v145 offset:49152
	ds_read_b128 v[212:215], v145 offset:50176
	ds_read_b128 v[216:219], v145 offset:51200
	ds_read_b128 v[220:223], v145 offset:52224
	ds_read_b128 v[224:227], v145 offset:53248
	ds_read_b128 v[228:231], v145 offset:54272
	ds_read_b128 v[232:235], v145 offset:55296
	ds_read_b128 v[236:239], v145 offset:56320
	global_load_lds_dwordx4 v0, s[84:85]
	s_add_i32 m0, s14, 0x2000
	s_add_u32 s12, s12, 0x160080
	s_addc_u32 s13, s13, 0
	s_add_i32 s14, s41, s25
	global_load_lds_dwordx4 v130, s[84:85]
	s_mov_b32 m0, s14
	s_nop 0
	global_load_lds_dwordx4 v0, s[12:13]
	s_add_i32 m0, s14, 0x2000
	s_nop 0
	global_load_lds_dwordx4 v130, s[12:13]
	s_mov_b32 m0, s30
	s_nop 0
	global_load_lds_dwordx4 v134, s[86:87]
	s_mov_b32 m0, s31
	s_nop 0
	global_load_lds_dwordx4 v132, s[86:87]
	s_waitcnt vmcnt(8)
	s_waitcnt lgkmcnt(0)
	s_barrier
	s_setprio 1
	s_waitcnt lgkmcnt(0)
	v_mfma_f32_16x16x32_bf16 v[62:65], v[146:149], v[208:211], v[62:65]
	v_mfma_f32_16x16x32_bf16 v[58:61], v[156:159], v[208:211], v[58:61]
	v_mfma_f32_16x16x32_bf16 v[46:49], v[146:149], v[216:219], v[46:49]
	v_mfma_f32_16x16x32_bf16 v[42:45], v[156:159], v[216:219], v[42:45]
	v_mfma_f32_16x16x32_bf16 v[30:33], v[146:149], v[224:227], v[30:33]
	v_mfma_f32_16x16x32_bf16 v[26:29], v[156:159], v[224:227], v[26:29]
	v_mfma_f32_16x16x32_bf16 v[14:17], v[146:149], v[232:235], v[14:17]
	v_mfma_f32_16x16x32_bf16 v[10:13], v[156:159], v[232:235], v[10:13]
	v_mfma_f32_16x16x32_bf16 v[62:65], v[150:153], v[212:215], v[62:65]
	v_mfma_f32_16x16x32_bf16 v[58:61], v[164:167], v[212:215], v[58:61]
	v_mfma_f32_16x16x32_bf16 v[46:49], v[150:153], v[220:223], v[46:49]
	v_mfma_f32_16x16x32_bf16 v[42:45], v[164:167], v[220:223], v[42:45]
	v_mfma_f32_16x16x32_bf16 v[30:33], v[150:153], v[228:231], v[30:33]
	v_mfma_f32_16x16x32_bf16 v[26:29], v[164:167], v[228:231], v[26:29]
	v_mfma_f32_16x16x32_bf16 v[14:17], v[150:153], v[236:239], v[14:17]
	v_mfma_f32_16x16x32_bf16 v[10:13], v[164:167], v[236:239], v[10:13]
	s_setprio 0
	s_setprio 1
	v_mfma_f32_16x16x32_bf16 v[54:57], v[172:175], v[208:211], v[54:57]
	v_mfma_f32_16x16x32_bf16 v[50:53], v[200:203], v[208:211], v[50:53]
	v_mfma_f32_16x16x32_bf16 v[38:41], v[172:175], v[216:219], v[38:41]
	v_mfma_f32_16x16x32_bf16 v[34:37], v[200:203], v[216:219], v[34:37]
	v_mfma_f32_16x16x32_bf16 v[22:25], v[172:175], v[224:227], v[22:25]
	v_mfma_f32_16x16x32_bf16 v[18:21], v[200:203], v[224:227], v[18:21]
	v_mfma_f32_16x16x32_bf16 v[6:9], v[172:175], v[232:235], v[6:9]
	v_mfma_f32_16x16x32_bf16 v[2:5], v[200:203], v[232:235], v[2:5]
	v_mfma_f32_16x16x32_bf16 v[54:57], v[180:183], v[212:215], v[54:57]
	v_mfma_f32_16x16x32_bf16 v[50:53], v[204:207], v[212:215], v[50:53]
	v_mfma_f32_16x16x32_bf16 v[38:41], v[180:183], v[220:223], v[38:41]
	v_mfma_f32_16x16x32_bf16 v[34:37], v[204:207], v[220:223], v[34:37]
	v_mfma_f32_16x16x32_bf16 v[22:25], v[180:183], v[228:231], v[22:25]
	v_mfma_f32_16x16x32_bf16 v[18:21], v[204:207], v[228:231], v[18:21]
	v_mfma_f32_16x16x32_bf16 v[6:9], v[180:183], v[236:239], v[6:9]
	v_mfma_f32_16x16x32_bf16 v[2:5], v[204:207], v[236:239], v[2:5]
	s_setprio 0
	s_barrier
	s_add_i32 s39, s39, 2
	s_add_u32 s10, s10, 0x100
	s_addc_u32 s11, s11, 0
	s_cmpk_gt_u32 s39, 0x55
